# v108 + diff stage loop: V pieces of the next stage staged with LDS-DMA (4 ds_write_b128 fewer per wave per stage before the stage barrier)
# speedup vs baseline: 1.0088x; 1.0040x over previous
; __device__ __forceinline__ int opaque_tid() { int t = (int)threadIdx.x; asm volatile("" : "+v"(t)); return t; }
; #define LAS __attribute__((address_space(3)))
; __device__ __forceinline__ int opaque_bx() { int b = (int)blockIdx.x; asm volatile("" : "+s"(b)); return b; }
; __device__ __forceinline__ KP kparams() { KP p = (KP)__builtin_amdgcn_kernarg_segment_ptr(); asm volatile("" : "+s"(p)); return p; }
; __device__ __forceinline__ void diff_phase(LAS unsigned char* lds, int L) {
;     ...
;     const KP P = kparams(); const int tid = opaque_tid(), lane = tid & 63, wave = __builtin_amdgcn_readfirstlane(tid >> 6);
;     const int r32 = lane & 31, hi = lane >> 5, map = wave >> 2, wq = wave & 3;
;     const int bx = opaque_bx(), vcu = (bx & 7) * 32 + (bx >> 3), xcd = vcu >> 5, grp = (vcu & 31) >> 3, mi = vcu & 7, eo = L >> 1;
;     unsigned char* ws = P->ws;
;     const bf16* Qb = (const bf16*)(ws + WS_Q); const bf16* Kb = (const bf16*)(ws + WS_K); const bf16* Vb = (const bf16*)(ws + WS_V); bf16* Ob = (bf16*)(ws + WS_O);
;     LAS float* dtab = (LAS float*)(lds + OFF_TAB);
;     const float lam_init = 0.8f - 0.6f * __builtin_amdgcn_exp2f(-0.3f * LOG2E * (float)L);
;     const float s1 = wave_sum(P->lq1[eo * 64 + lane] * P->lk1[eo * 64 + lane]), s2 = wave_sum(P->lq2[eo * 64 + lane] * P->lk2[eo * 64 + lane]);
;     const float lam = __builtin_amdgcn_exp2f(s1 * LOG2E) - __builtin_amdgcn_exp2f(s2 * LOG2E) + lam_init;
;     const int ksub = wave >> 2, krow0 = 32 * (wave & 3) + (lane >> 3);
;     const int klds = ksub * DKS + krow0 * 144 + (lane & 7) * 16;
;     const int vtile = wave >> 2, vdg = wave & 3, vkey0 = 64 * vtile + (lane >> 2);
;     const int vlds = DVO + vtile * 16384 + vdg * 4096 + 16 * lane;
;     ...
;             const float* sg = P->subln_g + eo * 128 + 4 * hi;
.LBB0_175:
	s_or_b64 exec, exec, s[38:39]
	s_andn2_b64 vcc, exec, s[36:37]
	s_mov_b64 s[4:5], -1
	s_waitcnt lgkmcnt(0)
	s_barrier
	s_cbranch_vccnz .LBB0_211
	s_mov_b64 s[8:9], s[60:61]
	v_mov_b32_e32 v3, v197
	s_mov_b32 s4, s57
	s_load_dwordx8 s[12:19], s[8:9], 0x58
	v_and_b32_e32 v6, 63, v3
	s_lshr_b32 s3, s78, 1
	v_lshl_or_b32 v0, s3, 6, v6
	v_mov_b32_e32 v1, v2
	v_lshlrev_b64 v[0:1], 2, v[0:1]
	s_waitcnt lgkmcnt(0)
	v_lshl_add_u64 v[4:5], s[12:13], 0, v[0:1]
	global_load_dword v7, v[4:5], off
	v_lshl_add_u64 v[4:5], s[14:15], 0, v[0:1]
	global_load_dword v8, v[4:5], off
	v_lshl_add_u64 v[4:5], s[16:17], 0, v[0:1]
	v_lshl_add_u64 v[0:1], s[18:19], 0, v[0:1]
	global_load_dword v4, v[4:5], off
	s_load_dwordx2 s[10:11], s[8:9], 0xb0
	global_load_dword v1, v[0:1], off
	v_readfirstlane_b32 s6, v3
	s_lshl_b32 s7, s4, 5
	s_ashr_i32 s21, s4, 3
	s_ashr_i32 s24, s6, 8
	s_bfe_u32 s26, s6, 0x20006
	s_and_b32 s7, s7, 0xe0
	s_bfe_u32 s36, s21, 0x20003
	s_and_b32 s37, s21, 7
	s_waitcnt lgkmcnt(0)
	s_add_u32 s12, s10, 0xa400000
	s_addc_u32 s13, s11, 0
	s_add_u32 s14, s10, 0xe400000
	s_addc_u32 s15, s11, 0
	s_add_u32 s16, s10, 0x12400000
	s_addc_u32 s17, s11, 0
	s_add_u32 s18, s10, 0x16400000
	v_bfe_u32 v11, v3, 3, 3
	v_bfe_u32 v13, v3, 2, 4
	s_addc_u32 s19, s11, 0
	s_lshl_b32 s39, s26, 5
	s_lshl_b32 s20, s24, 6
	v_or_b32_e32 v176, s39, v11
	v_or_b32_e32 v178, s20, v13
	v_sub_u32_e32 v14, 0xcf, v3
	v_cvt_f32_u32_e32 v5, s78
	v_and_b32_e32 v12, 7, v3
	v_cvt_f32_u32_e32 v17, v14
	s_mul_i32 s38, s24, 0x4800
	v_lshlrev_b32_e32 v16, 3, v12
	v_lshl_or_b32 v12, v12, 4, s38
	v_mad_u32_u24 v207, v176, s67, v12
	v_mul_f32_e32 v5, 0xbedd9914, v5
	v_mul_f32_e32 v17, 0x3d800000, v17
	v_exp_f32_e32 v5, v5
	v_log_f32_e32 v17, v17
	s_add_i32 s7, s7, s21
	v_mov_b32_e32 v9, 0x3f4ccccd
	s_ashr_i32 s7, s7, 1
	v_fmamk_f32 v5, v5, 0xbf19999a, v9
	v_mul_f32_e32 v9, 0x40aaaaab, v17
	s_xor_b32 s40, s37, 15
	s_ashr_i32 s21, s20, 31
	s_and_b32 s41, s7, -16
	v_cvt_i32_f32_e32 v9, v9
	s_cmpk_lt_u32 s6, 0x100
	s_cselect_b64 s[22:23], -1, 0
	s_sub_i32 s101, 3, s26
	s_cmp_eq_u32 s24, 1
	s_cselect_b32 s101, s101, s26
	s_lshl_b32 s6, s101, 14
	s_add_i32 s6, s6, 0
	v_lshlrev_b32_e32 v15, 4, v6
	s_cmp_eq_u32 s24, 1
	v_lshl_or_b32 v18, s24, 14, v15
	s_movk_i32 s7, 0xc0
	s_cselect_b64 s[24:25], -1, 0
	s_lshl_b32 s72, s3, 7
	s_movk_i32 s3, 0xff7f
	v_cmp_gt_u32_e32 vcc, s7, v3
	v_lshl_add_u32 v216, v6, 2, s6
	v_and_b32_e32 v177, 31, v3
	v_bfe_u32 v10, v3, 5, 1
	v_lshlrev_b32_e32 v0, 3, v3
	v_and_b32_e32 v181, 24, v0
	v_lshlrev_b32_e32 v211, 4, v10
	s_movk_i32 s5, 0x140
	v_lshlrev_b32_e32 v0, 3, v10
	v_ashrrev_i32_e32 v179, 31, v178
	v_readlane_b32 s1, v254, 0
	v_cmp_gt_i32_e64 s[4:5], s5, v3
	v_lshl_or_b32 v204, s26, 12, v18
	v_or_b32_e32 v205, s20, v16
	v_or_b32_e32 v206, s39, v181
	v_lshl_add_u32 v209, v3, 2, s1
	v_mul_u32_u24_e32 v210, 0x90, v177
	v_lshlrev_b32_e32 v213, 8, v10
	v_and_b32_e32 v214, 0xc0, v15
	v_sub_f32_e32 v217, 1.0, v5
	s_waitcnt vmcnt(0)
	v_mul_f32_e32 v11, v7, v8
	v_lshlrev_b32_e32 v180, 2, v10
	v_lshlrev_b32_e32 v182, 11, v176
	v_mov_b32_dpp v11, v11 quad_perm:[1,0,3,2] row_mask:0xf bank_mask:0xf bound_ctrl:1
	v_fmac_f32_e32 v11, v7, v8
	v_mul_f32_e32 v13, v4, v1
	v_mov_b32_e32 v183, v2
	v_lshlrev_b64 v[184:185], 11, v[178:179]
	v_mov_b32_dpp v13, v13 quad_perm:[1,0,3,2] row_mask:0xf bank_mask:0xf bound_ctrl:1
	v_fmac_f32_e32 v13, v4, v1
	v_add_f32_dpp v1, v11, v11 quad_perm:[2,3,0,1] row_mask:0xf bank_mask:0xf bound_ctrl:1
	s_mov_b32 s42, 0
	v_add_f32_dpp v4, v13, v13 quad_perm:[2,3,0,1] row_mask:0xf bank_mask:0xf bound_ctrl:1
	v_add_f32_dpp v1, v1, v1 row_half_mirror row_mask:0xf bank_mask:0xf bound_ctrl:1
	v_lshlrev_b32_e32 v186, 1, v0
	v_add_f32_dpp v4, v4, v4 row_half_mirror row_mask:0xf bank_mask:0xf bound_ctrl:1
	v_add_f32_dpp v1, v1, v1 row_mirror row_mask:0xf bank_mask:0xf bound_ctrl:1
	ds_swizzle_b32 v7, v1 offset:swizzle(SWAP,16)
	v_add_f32_dpp v4, v4, v4 row_mirror row_mask:0xf bank_mask:0xf bound_ctrl:1
	ds_swizzle_b32 v8, v4 offset:swizzle(SWAP,16)
	s_mov_b32 s43, 0
	s_waitcnt lgkmcnt(1)
	v_add_f32_e32 v1, v1, v7
	v_mov_b32_e32 v7, v1
	s_waitcnt lgkmcnt(0)
	v_add_f32_e32 v4, v4, v8
	v_mov_b32_e32 v8, v1
	v_mov_b32_e32 v11, v4
	v_mov_b32_e32 v12, v4
	v_permlane32_swap_b32_e32 v7, v8
	s_nop 0
	v_permlane32_swap_b32_e32 v11, v12
	v_xor_b32_e32 v7, v7, v8
	v_xor_b32_e32 v8, v11, v12
	v_xor_b32_e32 v7, v7, v1
	v_xor_b32_e32 v8, v8, v4
	v_add_f32_e32 v1, v1, v7
	v_add_f32_e32 v4, v4, v8
	v_mul_f32_e32 v1, 0x3fb8aa3b, v1
	v_mul_f32_e32 v4, 0x3fb8aa3b, v4
	v_exp_f32_e32 v1, v1
	v_exp_f32_e32 v4, v4
	v_min_i32_e32 v7, 15, v9
	v_sub_f32_e32 v1, v1, v4
	v_add_f32_e32 v1, v5, v1
	v_cndmask_b32_e64 v215, v1, 1.0, s[22:23]
	v_add_u32_e32 v1, 0xffffff30, v3
	v_add_u32_e32 v4, 16, v7
	v_cmp_lt_u32_e64 s[6:7], s3, v1
	s_movk_i32 s3, 0xcf
	v_cndmask_b32_e32 v4, v14, v4, vcc
	v_cmp_lt_i32_e32 vcc, s3, v3
	s_lshl_b32 s3, s36, 7
	s_add_i32 s27, s3, s20
	s_or_b32 s3, s3, s39
	s_lshl_b32 s39, s101, 5
	v_lshlrev_b32_e32 v1, 2, v177
	v_or_b32_e32 v220, s3, v181
	v_sub_u32_e32 v1, v211, v1
	s_lshl_b32 s3, s101, 7
	v_readfirstlane_b32 s101, v204
	v_lshlrev_b32_e32 v208, 3, v4
	v_lshlrev_b32_e32 v4, 1, v3
	v_subrev_u32_e32 v1, s3, v1
	s_add_i32 s101, s101, 0x9000
	v_and_b32_e32 v212, 32, v4
	v_cndmask_b32_e32 v218, 0, v249, vcc
	v_or_b32_e32 v219, s27, v16
	v_add_u32_e32 v221, 0, v1
	s_lshl_b64 s[26:27], s[72:73], 2
	s_load_dwordx2 s[44:45], s[8:9], 0x78
	v_cmp_gt_u32_e32 vcc, 0x80, v197
	s_waitcnt lgkmcnt(0)
	s_add_u32 s44, s44, s26
	s_addc_u32 s45, s45, s27
	s_and_saveexec_b64 s[46:47], vcc
	v_lshlrev_b32_e32 v0, 2, v197
	global_load_dword v1, v0, s[44:45]
	v_add_u32_e32 v0, 0x22580, v0
	s_waitcnt vmcnt(0)
	ds_write_b32 v0, v1
	s_or_b64 exec, exec, s[46:47]
	s_mov_b32 s100, 0
	s_branch .LBB0_178

; #define DF_LOAD(T) do { const bf16* kg = Kb + (tokb + 128 * (T) + krow0) * 1024 + kgcol; const bf16* vg = Vb + (tokb + 128 * (T) + vkey0) * 1024 + vgcol; \
;         _Pragma("unroll") for (int c_ = 0; c_ < 4; ++c_) { kreg[c_] = *(const u32x4*)(kg + c_ * 8 * 1024); vreg[c_] = *(const u32x4*)(vg + c_ * 16 * 1024); } } while (0)
; __device__ __forceinline__ void diff_phase(LAS unsigned char* lds, int L) {
;     ...
;             if (it + 1 < NT) DF_LOAD(T - 1);
.LBB0_186:
	s_cmp_lt_u32 s52, s35
	s_cselect_b64 s[30:31], -1, 0
	s_cmp_ge_u32 s52, s35
	s_cbranch_scc1 .LBB0_188
	s_bitcmp1_b32 s52, 0
	s_cselect_b32 s3, 0, 0x11000
	s_add_i32 s3, s3, s101
	s_add_u32 s44, s28, 0xe3c0000
	s_addc_u32 s45, s29, 0
	global_load_dwordx4 v[128:131], v190, s[44:45]
	s_mov_b32 m0, s3
	s_add_u32 s44, s28, 0x123c0000
	s_addc_u32 s45, s29, 0
	global_load_lds_dwordx4 v192, s[44:45]
	s_add_u32 s44, s28, 0xe3c4000
	s_addc_u32 s45, s29, 0
	global_load_dwordx4 v[140:143], v190, s[44:45]
	s_add_i32 m0, s3, 0x400
	s_add_u32 s44, s28, 0x123c8000
	s_addc_u32 s45, s29, 0
	global_load_lds_dwordx4 v192, s[44:45]
	s_add_u32 s44, s28, 0xe3c8000
	s_addc_u32 s45, s29, 0
	global_load_dwordx4 v[160:163], v190, s[44:45]
	s_add_i32 m0, s3, 0x800
	s_add_u32 s44, s28, 0x123d0000
	s_addc_u32 s45, s29, 0
	global_load_lds_dwordx4 v192, s[44:45]
	s_add_u32 s44, s28, 0xe3cc000
	s_addc_u32 s45, s29, 0
	global_load_dwordx4 v[168:171], v190, s[44:45]
	s_add_i32 m0, s3, 0xc00
	s_add_u32 s44, s28, 0x123d8000
	s_addc_u32 s45, s29, 0
	global_load_lds_dwordx4 v192, s[44:45]

; #define DF_STORE(sb) do { LAS unsigned char* s_ = lds + (sb) * DST; \
;         _Pragma("unroll") for (int c_ = 0; c_ < 4; ++c_) { *(LAS u32x4*)(s_ + klds + c_ * 8 * 144) = kreg[c_]; *(LAS u32x4*)(s_ + vlds + c_ * 1024) = vreg[c_]; } } while (0)
; __device__ __forceinline__ void diff_phase(LAS unsigned char* lds, int L) {
;     ...
;             if (it + 1 < NT) DF_STORE((it + 1) & 1);
.LBB0_205:
	s_bitcmp1_b32 s52, 0
	s_cselect_b32 s3, 0x11000, 0
	v_add_u32_e32 v0, s3, v207
	s_waitcnt vmcnt(0)
	ds_write_b128 v0, v[128:131]
	ds_write_b128 v0, v[140:143] offset:1152
	ds_write_b128 v0, v[160:163] offset:2304
	ds_write_b128 v0, v[168:171] offset:3456
	s_branch .LBB0_185
